# dsa_prep: k-head load also issued with the four q-head loads (5 loads in flight per row)
# baseline (speedup 1.0000x reference)
; __device__ __forceinline__ unsigned pk2(float lo, float hi) { const f32x2 v = {lo, hi}; const hwbf16x2 b = __builtin_convertvector(v, hwbf16x2); return __builtin_bit_cast(unsigned, b); }
; __device__ __forceinline__ void dsa_prep(const Args& a, unsigned char* lds, int tid) {
;     ...
;         for (int i = 0; i < 8; ++i) {
;             const int row = t0 + 8 * w + i;
;             const bf16* src = QKVI + (size_t)row * QKVI_LD;
; #pragma unroll
;             for (int j = 0; j < 5; ++j) {
;                 const int hh = j * 4 + grp, col = hh * 64 + 4 * sub;
;                 const u32x2 x = *(const u32x2*)(src + col);
;                 f32x4 v = (f32x4){bflo(x.x), bfhi(x.x), bflo(x.y), bfhi(x.y)};
;                 float ss = (v.x * v.x + v.y * v.y) + (v.z * v.z + v.w * v.w);
;                 ss = row16_sum(ss);
;                 const float rstd = __builtin_amdgcn_rsqf(ss * (1.f / 64.f) + 1e-6f);
;                 if (j < 4) { v = v * rstd * qn * QSCALE; u32x2 o; o.x = pk2(v.x, v.y); o.y = pk2(v.z, v.w); *(u32x2*)(QN + (size_t)row * D + col) = o; }
;                 else { v = v * rstd * kn; u32x2 o; o.x = pk2(v.x, v.y); o.y = pk2(v.z, v.w); *(u32x2*)(KN + (size_t)row * 256 + (col - 1024)) = o; }
.LBB0_575:
	v_lshl_add_u64 v[58:59], s[16:17], 0, v[52:53]
	v_add_co_u32_e32 v58, vcc, 0x9d00000, v58
	v_lshl_add_u64 v[62:63], s[16:17], 0, v[50:51]
	s_nop 0
	v_addc_co_u32_e32 v59, vcc, 0, v59, vcc
	global_load_dwordx2 v[100:101], v[58:59], off
	global_load_dwordx2 v[102:103], v[58:59], off offset:512
	global_load_dwordx2 v[104:105], v[58:59], off offset:1024
	global_load_dwordx2 v[60:61], v[58:59], off offset:1536
	global_load_dwordx2 v[106:107], v[58:59], off offset:2048
	s_mov_b32 s12, 0x12d00000
	v_add_co_u32_e32 v62, vcc, s12, v62
	s_waitcnt vmcnt(4)
	v_lshlrev_b32_e32 v65, 16, v101
	v_lshlrev_b32_e32 v64, 16, v100
	v_and_b32_e32 v101, 0xffff0000, v101
	v_and_b32_e32 v100, 0xffff0000, v100
	v_pk_mul_f32 v[66:67], v[100:101], v[100:101]
	v_mov_b32_e32 v72, v65
	v_pk_fma_f32 v[66:67], v[64:65], v[64:65], v[66:67]
	v_mov_b32_e32 v73, v101
	v_add_f32_e32 v29, v66, v67
	v_mov_b32_e32 v65, v100
	v_addc_co_u32_e32 v63, vcc, 0, v63, vcc
	v_add_f32_dpp v29, v29, v29 quad_perm:[1,0,3,2] row_mask:0xf bank_mask:0xf bound_ctrl:1
	s_nop 1
	v_add_f32_dpp v29, v29, v29 quad_perm:[2,3,0,1] row_mask:0xf bank_mask:0xf bound_ctrl:1
	s_nop 1
	v_add_f32_dpp v29, v29, v29 row_half_mirror row_mask:0xf bank_mask:0xf bound_ctrl:1
	s_nop 1
	v_add_f32_dpp v29, v29, v29 row_mirror row_mask:0xf bank_mask:0xf bound_ctrl:1
	v_fmamk_f32 v29, v29, 0x3c800000, v23
	v_rsq_f32_e32 v66, v29
	s_nop 0
	v_pk_mul_f32 v[100:101], v[66:67], v[72:73] op_sel_hi:[0,1]
	v_pk_mul_f32 v[64:65], v[66:67], v[64:65] op_sel_hi:[0,1]
	v_pk_mul_f32 v[64:65], v[0:1], v[64:65]
	v_pk_mul_f32 v[100:101], v[2:3], v[100:101]
	v_pk_mul_f32 v[64:65], v[64:65], s[8:9] op_sel_hi:[1,0]
	v_pk_mul_f32 v[100:101], v[100:101], s[8:9] op_sel_hi:[1,0]
	v_cvt_pk_bf16_f32 v64, v64, v65
	v_cvt_pk_bf16_f32 v65, v100, v101
	global_store_dwordx2 v[62:63], v[64:65], off
	s_waitcnt vmcnt(4)
	v_lshlrev_b32_e32 v65, 16, v103
	v_lshlrev_b32_e32 v64, 16, v102
	v_and_b32_e32 v103, 0xffff0000, v103
	v_and_b32_e32 v102, 0xffff0000, v102
	v_pk_mul_f32 v[66:67], v[102:103], v[102:103]
	v_mov_b32_e32 v72, v65
	v_pk_fma_f32 v[66:67], v[64:65], v[64:65], v[66:67]
	v_mov_b32_e32 v73, v103
	v_add_f32_e32 v29, v66, v67
	v_mov_b32_e32 v65, v102
	s_nop 0
	v_add_f32_dpp v29, v29, v29 quad_perm:[1,0,3,2] row_mask:0xf bank_mask:0xf bound_ctrl:1
	s_nop 1
	v_add_f32_dpp v29, v29, v29 quad_perm:[2,3,0,1] row_mask:0xf bank_mask:0xf bound_ctrl:1
	s_nop 1
	v_add_f32_dpp v29, v29, v29 row_half_mirror row_mask:0xf bank_mask:0xf bound_ctrl:1
	s_nop 1
	v_add_f32_dpp v29, v29, v29 row_mirror row_mask:0xf bank_mask:0xf bound_ctrl:1
	v_fmamk_f32 v29, v29, 0x3c800000, v23
	v_rsq_f32_e32 v66, v29
	s_nop 0
	v_pk_mul_f32 v[102:103], v[66:67], v[72:73] op_sel_hi:[0,1]
	v_pk_mul_f32 v[64:65], v[66:67], v[64:65] op_sel_hi:[0,1]
	v_pk_mul_f32 v[64:65], v[0:1], v[64:65]
	v_pk_mul_f32 v[102:103], v[2:3], v[102:103]
	v_pk_mul_f32 v[64:65], v[64:65], s[8:9] op_sel_hi:[1,0]
	v_pk_mul_f32 v[102:103], v[102:103], s[8:9] op_sel_hi:[1,0]
	v_cvt_pk_bf16_f32 v64, v64, v65
	v_cvt_pk_bf16_f32 v65, v102, v103
	global_store_dwordx2 v[62:63], v[64:65], off offset:512
	s_waitcnt vmcnt(4)
	v_lshlrev_b32_e32 v65, 16, v105
	v_lshlrev_b32_e32 v64, 16, v104
	v_and_b32_e32 v105, 0xffff0000, v105
	v_and_b32_e32 v104, 0xffff0000, v104
	v_pk_mul_f32 v[66:67], v[104:105], v[104:105]
	v_mov_b32_e32 v72, v65
	v_pk_fma_f32 v[66:67], v[64:65], v[64:65], v[66:67]
	v_mov_b32_e32 v73, v105
	v_add_f32_e32 v29, v66, v67
	v_mov_b32_e32 v65, v104
	s_nop 0
	v_add_f32_dpp v29, v29, v29 quad_perm:[1,0,3,2] row_mask:0xf bank_mask:0xf bound_ctrl:1
	s_nop 1
	v_add_f32_dpp v29, v29, v29 quad_perm:[2,3,0,1] row_mask:0xf bank_mask:0xf bound_ctrl:1
	s_nop 1
	v_add_f32_dpp v29, v29, v29 row_half_mirror row_mask:0xf bank_mask:0xf bound_ctrl:1
	s_nop 1
	v_add_f32_dpp v29, v29, v29 row_mirror row_mask:0xf bank_mask:0xf bound_ctrl:1
	v_fmamk_f32 v29, v29, 0x3c800000, v23
	v_rsq_f32_e32 v66, v29
	s_nop 0
	v_pk_mul_f32 v[104:105], v[66:67], v[72:73] op_sel_hi:[0,1]
	v_pk_mul_f32 v[64:65], v[66:67], v[64:65] op_sel_hi:[0,1]
	v_pk_mul_f32 v[64:65], v[0:1], v[64:65]
	v_pk_mul_f32 v[104:105], v[2:3], v[104:105]
	v_pk_mul_f32 v[64:65], v[64:65], s[8:9] op_sel_hi:[1,0]
	v_pk_mul_f32 v[104:105], v[104:105], s[8:9] op_sel_hi:[1,0]
	v_cvt_pk_bf16_f32 v64, v64, v65
	v_cvt_pk_bf16_f32 v65, v104, v105
	global_store_dwordx2 v[62:63], v[64:65], off offset:1024
	s_waitcnt vmcnt(4)
; __device__ __forceinline__ unsigned pk2(float lo, float hi) { const f32x2 v = {lo, hi}; const hwbf16x2 b = __builtin_convertvector(v, hwbf16x2); return __builtin_bit_cast(unsigned, b); }
; __device__ __forceinline__ void dsa_prep(const Args& a, unsigned char* lds, int tid) {
;     ...
;             for (int j = 0; j < 5; ++j) {
;                 const int hh = j * 4 + grp, col = hh * 64 + 4 * sub;
;                 const u32x2 x = *(const u32x2*)(src + col);
;                 f32x4 v = (f32x4){bflo(x.x), bfhi(x.x), bflo(x.y), bfhi(x.y)};
;                 float ss = (v.x * v.x + v.y * v.y) + (v.z * v.z + v.w * v.w);
;                 ss = row16_sum(ss);
;                 const float rstd = __builtin_amdgcn_rsqf(ss * (1.f / 64.f) + 1e-6f);
;                 if (j < 4) { v = v * rstd * qn * QSCALE; u32x2 o; o.x = pk2(v.x, v.y); o.y = pk2(v.z, v.w); *(u32x2*)(QN + (size_t)row * D + col) = o; }
;                 else { v = v * rstd * kn; u32x2 o; o.x = pk2(v.x, v.y); o.y = pk2(v.z, v.w); *(u32x2*)(KN + (size_t)row * 256 + (col - 1024)) = o; }
;             }
;             {
;                 const u32x2 x = *(const u32x2*)(src + 2048 + 4 * sub);
;                 f32x4 v = (f32x4){bflo(x.x), bfhi(x.x), bflo(x.y), bfhi(x.y)};
;                 float ss = (v.x * v.x + v.y * v.y) + (v.z * v.z + v.w * v.w);
;                 ss = row16_sum(ss);
;                 const float rstd = __builtin_amdgcn_rsqf(ss * (1.f / 64.f) + 1e-6f);
;                 v = v * rstd * ikn;
;                 if (grp == 0) { u32x2 o; o.x = pk2(v.x, v.y); o.y = pk2(v.z, v.w); *(u32x2*)(IKN + (size_t)row * 64 + 4 * sub) = o; }
	v_lshlrev_b32_e32 v65, 16, v61
	v_lshlrev_b32_e32 v64, 16, v60
	v_and_b32_e32 v61, 0xffff0000, v61
	v_and_b32_e32 v60, 0xffff0000, v60
	v_pk_mul_f32 v[66:67], v[60:61], v[60:61]
	v_mov_b32_e32 v72, v65
	v_pk_fma_f32 v[66:67], v[64:65], v[64:65], v[66:67]
	v_mov_b32_e32 v73, v61
	v_add_f32_e32 v29, v66, v67
	v_mov_b32_e32 v65, v60
	s_nop 0
	v_add_f32_dpp v29, v29, v29 quad_perm:[1,0,3,2] row_mask:0xf bank_mask:0xf bound_ctrl:1
	s_nop 1
	v_add_f32_dpp v29, v29, v29 quad_perm:[2,3,0,1] row_mask:0xf bank_mask:0xf bound_ctrl:1
	s_nop 1
	v_add_f32_dpp v29, v29, v29 row_half_mirror row_mask:0xf bank_mask:0xf bound_ctrl:1
	s_nop 1
	v_add_f32_dpp v29, v29, v29 row_mirror row_mask:0xf bank_mask:0xf bound_ctrl:1
	v_fmamk_f32 v29, v29, 0x3c800000, v23
	v_rsq_f32_e32 v66, v29
	s_nop 0
	v_pk_mul_f32 v[60:61], v[66:67], v[72:73] op_sel_hi:[0,1]
	v_pk_mul_f32 v[64:65], v[66:67], v[64:65] op_sel_hi:[0,1]
	v_pk_mul_f32 v[64:65], v[0:1], v[64:65]
	v_pk_mul_f32 v[60:61], v[2:3], v[60:61]
	v_pk_mul_f32 v[64:65], v[64:65], s[8:9] op_sel_hi:[1,0]
	v_pk_mul_f32 v[60:61], v[60:61], s[8:9] op_sel_hi:[1,0]
	v_cvt_pk_bf16_f32 v64, v64, v65
	v_cvt_pk_bf16_f32 v65, v60, v61
	global_store_dwordx2 v[62:63], v[64:65], off offset:1536
	v_lshl_add_u64 v[60:61], s[16:17], 0, v[48:49]
	v_lshl_add_u64 v[62:63], s[16:17], 0, v[54:55]
	s_waitcnt vmcnt(4)
	v_lshlrev_b32_e32 v65, 16, v107
	v_lshlrev_b32_e32 v64, 16, v106
	v_and_b32_e32 v107, 0xffff0000, v107
	v_and_b32_e32 v106, 0xffff0000, v106
	v_pk_mul_f32 v[66:67], v[106:107], v[106:107]
	v_mov_b32_e32 v72, v64
	v_pk_fma_f32 v[66:67], v[64:65], v[64:65], v[66:67]
	v_mov_b32_e32 v73, v106
	v_add_f32_e32 v29, v66, v67
	v_mov_b32_e32 v106, v65
	s_nop 0
	v_add_f32_dpp v29, v29, v29 quad_perm:[1,0,3,2] row_mask:0xf bank_mask:0xf bound_ctrl:1
	s_nop 1
	v_add_f32_dpp v29, v29, v29 quad_perm:[2,3,0,1] row_mask:0xf bank_mask:0xf bound_ctrl:1
	s_nop 1
	v_add_f32_dpp v29, v29, v29 row_half_mirror row_mask:0xf bank_mask:0xf bound_ctrl:1
	s_nop 1
	v_add_f32_dpp v29, v29, v29 row_mirror row_mask:0xf bank_mask:0xf bound_ctrl:1
	v_fmamk_f32 v29, v29, 0x3c800000, v23
	v_rsq_f32_e32 v66, v29
	s_nop 0
	v_pk_mul_f32 v[64:65], v[66:67], v[72:73] op_sel_hi:[0,1]
	v_pk_mul_f32 v[106:107], v[66:67], v[106:107] op_sel_hi:[0,1]
	v_pk_mul_f32 v[106:107], v[6:7], v[106:107]
	v_pk_mul_f32 v[64:65], v[4:5], v[64:65]
	s_nop 0
	v_cvt_pk_bf16_f32 v64, v64, v65
	v_cvt_pk_bf16_f32 v65, v106, v107
	global_store_dwordx2 v[60:61], v[64:65], off
	global_load_dwordx2 v[58:59], v[62:63], off
	s_waitcnt vmcnt(0)
	v_lshlrev_b32_e32 v60, 16, v58
	v_and_b32_e32 v61, 0xffff0000, v58
	v_lshlrev_b32_e32 v58, 16, v59
	v_and_b32_e32 v59, 0xffff0000, v59
	v_mul_f32_e32 v29, v61, v61
	v_mul_f32_e32 v41, v59, v59
	v_fmac_f32_e32 v29, v60, v60
	v_fmac_f32_e32 v41, v58, v58
	v_add_f32_e32 v29, v29, v41
	s_nop 1
	v_add_f32_dpp v29, v29, v29 quad_perm:[1,0,3,2] row_mask:0xf bank_mask:0xf bound_ctrl:1
	s_nop 1
	v_add_f32_dpp v29, v29, v29 quad_perm:[2,3,0,1] row_mask:0xf bank_mask:0xf bound_ctrl:1
	s_nop 1
	v_add_f32_dpp v29, v29, v29 row_half_mirror row_mask:0xf bank_mask:0xf bound_ctrl:1
	s_nop 1
	v_mov_b32_dpp v41, v29 row_mirror row_mask:0xf bank_mask:0xf bound_ctrl:1
	s_and_saveexec_b64 s[12:13], s[0:1]
	s_cbranch_execz .LBB0_577
	v_add_f32_e32 v29, v29, v41
	v_fmamk_f32 v29, v29, 0x3c800000, v23
	v_rsq_f32_e32 v62, v29
	s_nop 0
	v_pk_mul_f32 v[60:61], v[60:61], v[62:63] op_sel_hi:[1,0]
	v_pk_mul_f32 v[58:59], v[58:59], v[62:63] op_sel_hi:[1,0]
	v_pk_mul_f32 v[60:61], v[8:9], v[60:61]
	v_pk_mul_f32 v[58:59], v[10:11], v[58:59]
	v_cvt_pk_bf16_f32 v60, v60, v61
	v_cvt_pk_bf16_f32 v61, v58, v59
	v_lshl_add_u64 v[58:59], s[16:17], 0, v[44:45]
	global_store_dwordx2 v[58:59], v[60:61], off

; __device__ __forceinline__ unsigned pk2(float lo, float hi) { const f32x2 v = {lo, hi}; const hwbf16x2 b = __builtin_convertvector(v, hwbf16x2); return __builtin_bit_cast(unsigned, b); }
; __device__ __forceinline__ void dsa_prep(const Args& a, unsigned char* lds, int tid) {
;     ...
;         for (int i = 0; i < 8; ++i) {
;             const int row = t0 + 8 * w + i;
;             const bf16* src = QKVI + (size_t)row * QKVI_LD;
; #pragma unroll
;             for (int j = 0; j < 5; ++j) {
;                 const int hh = j * 4 + grp, col = hh * 64 + 4 * sub;
;                 const u32x2 x = *(const u32x2*)(src + col);
;                 f32x4 v = (f32x4){bflo(x.x), bfhi(x.x), bflo(x.y), bfhi(x.y)};
;                 float ss = (v.x * v.x + v.y * v.y) + (v.z * v.z + v.w * v.w);
;                 ss = row16_sum(ss);
;                 const float rstd = __builtin_amdgcn_rsqf(ss * (1.f / 64.f) + 1e-6f);
;                 if (j < 4) { v = v * rstd * qn * QSCALE; u32x2 o; o.x = pk2(v.x, v.y); o.y = pk2(v.z, v.w); *(u32x2*)(QN + (size_t)row * D + col) = o; }
;                 else { v = v * rstd * kn; u32x2 o; o.x = pk2(v.x, v.y); o.y = pk2(v.z, v.w); *(u32x2*)(KN + (size_t)row * 256 + (col - 1024)) = o; }
;             }
.LBB0_579:
	s_or_b64 exec, exec, s[12:13]
	v_readlane_b32 s12, v248, 61
	v_add_u32_e32 v29, s6, v28
	v_readlane_b32 s13, v248, 62
	v_add_u32_e32 v60, 1, v29
	v_ashrrev_i32_e32 v61, 31, v60
	v_mov_b64_e32 v[58:59], s[12:13]
	v_mad_i64_i32 v[62:63], s[12:13], v60, s22, v[58:59]
	v_lshl_add_u64 v[58:59], v[62:63], 0, v[12:13]
	global_load_dwordx2 v[100:101], v[58:59], off
	global_load_dwordx2 v[102:103], v[58:59], off offset:512
	global_load_dwordx2 v[104:105], v[58:59], off offset:1024
	global_load_dwordx2 v[64:65], v[58:59], off offset:1536
	global_load_dwordx2 v[106:107], v[58:59], off offset:2048
	v_lshlrev_b64 v[66:67], 11, v[60:61]
	v_lshl_add_u64 v[66:67], v[26:27], 0, v[66:67]
	s_waitcnt vmcnt(4)
	v_lshlrev_b32_e32 v73, 16, v101
	v_lshlrev_b32_e32 v72, 16, v100
	v_and_b32_e32 v101, 0xffff0000, v101
	v_and_b32_e32 v100, 0xffff0000, v100
	v_pk_mul_f32 v[74:75], v[100:101], v[100:101]
	v_mov_b32_e32 v76, v73
	v_pk_fma_f32 v[74:75], v[72:73], v[72:73], v[74:75]
	v_mov_b32_e32 v77, v101
	v_add_f32_e32 v41, v74, v75
	v_mov_b32_e32 v73, v100
	s_nop 0
	v_add_f32_dpp v41, v41, v41 quad_perm:[1,0,3,2] row_mask:0xf bank_mask:0xf bound_ctrl:1
	s_nop 1
	v_add_f32_dpp v41, v41, v41 quad_perm:[2,3,0,1] row_mask:0xf bank_mask:0xf bound_ctrl:1
	s_nop 1
	v_add_f32_dpp v41, v41, v41 row_half_mirror row_mask:0xf bank_mask:0xf bound_ctrl:1
	s_nop 1
	v_add_f32_dpp v41, v41, v41 row_mirror row_mask:0xf bank_mask:0xf bound_ctrl:1
	v_fmamk_f32 v41, v41, 0x3c800000, v23
	v_rsq_f32_e32 v74, v41
	s_nop 0
	v_pk_mul_f32 v[100:101], v[74:75], v[76:77] op_sel_hi:[0,1]
	v_pk_mul_f32 v[72:73], v[74:75], v[72:73] op_sel_hi:[0,1]
	v_pk_mul_f32 v[72:73], v[0:1], v[72:73]
	v_pk_mul_f32 v[100:101], v[2:3], v[100:101]
	v_pk_mul_f32 v[72:73], v[72:73], s[8:9] op_sel_hi:[1,0]
	v_pk_mul_f32 v[100:101], v[100:101], s[8:9] op_sel_hi:[1,0]
	v_cvt_pk_bf16_f32 v72, v72, v73
	v_cvt_pk_bf16_f32 v73, v100, v101
	global_store_dwordx2 v[66:67], v[72:73], off
	s_waitcnt vmcnt(4)
	v_lshlrev_b32_e32 v73, 16, v103
	v_lshlrev_b32_e32 v72, 16, v102
	v_and_b32_e32 v103, 0xffff0000, v103
	v_and_b32_e32 v102, 0xffff0000, v102
	v_pk_mul_f32 v[74:75], v[102:103], v[102:103]
	v_mov_b32_e32 v76, v73
	v_pk_fma_f32 v[74:75], v[72:73], v[72:73], v[74:75]
	v_mov_b32_e32 v77, v103
	v_add_f32_e32 v41, v74, v75
	v_mov_b32_e32 v73, v102
	s_nop 0
	v_add_f32_dpp v41, v41, v41 quad_perm:[1,0,3,2] row_mask:0xf bank_mask:0xf bound_ctrl:1
	s_nop 1
	v_add_f32_dpp v41, v41, v41 quad_perm:[2,3,0,1] row_mask:0xf bank_mask:0xf bound_ctrl:1
	s_nop 1
	v_add_f32_dpp v41, v41, v41 row_half_mirror row_mask:0xf bank_mask:0xf bound_ctrl:1
	s_nop 1
	v_add_f32_dpp v41, v41, v41 row_mirror row_mask:0xf bank_mask:0xf bound_ctrl:1
	v_fmamk_f32 v41, v41, 0x3c800000, v23
	v_rsq_f32_e32 v74, v41
	s_nop 0
	v_pk_mul_f32 v[102:103], v[74:75], v[76:77] op_sel_hi:[0,1]
	v_pk_mul_f32 v[72:73], v[74:75], v[72:73] op_sel_hi:[0,1]
	v_pk_mul_f32 v[72:73], v[0:1], v[72:73]
	v_pk_mul_f32 v[102:103], v[2:3], v[102:103]
	v_pk_mul_f32 v[72:73], v[72:73], s[8:9] op_sel_hi:[1,0]
	v_pk_mul_f32 v[102:103], v[102:103], s[8:9] op_sel_hi:[1,0]
	v_cvt_pk_bf16_f32 v72, v72, v73
	v_cvt_pk_bf16_f32 v73, v102, v103
	global_store_dwordx2 v[66:67], v[72:73], off offset:512
	s_waitcnt vmcnt(4)
	v_lshlrev_b32_e32 v73, 16, v105
	v_lshlrev_b32_e32 v72, 16, v104
	v_and_b32_e32 v105, 0xffff0000, v105
	v_and_b32_e32 v104, 0xffff0000, v104
	v_pk_mul_f32 v[74:75], v[104:105], v[104:105]
	v_mov_b32_e32 v76, v73
	v_pk_fma_f32 v[74:75], v[72:73], v[72:73], v[74:75]
	v_mov_b32_e32 v77, v105
	v_add_f32_e32 v41, v74, v75
	v_mov_b32_e32 v73, v104
	s_nop 0
	v_add_f32_dpp v41, v41, v41 quad_perm:[1,0,3,2] row_mask:0xf bank_mask:0xf bound_ctrl:1
	s_nop 1
	v_add_f32_dpp v41, v41, v41 quad_perm:[2,3,0,1] row_mask:0xf bank_mask:0xf bound_ctrl:1
	s_nop 1
	v_add_f32_dpp v41, v41, v41 row_half_mirror row_mask:0xf bank_mask:0xf bound_ctrl:1
	s_nop 1
	v_add_f32_dpp v41, v41, v41 row_mirror row_mask:0xf bank_mask:0xf bound_ctrl:1
	v_fmamk_f32 v41, v41, 0x3c800000, v23
	v_rsq_f32_e32 v74, v41
	s_nop 0
	v_pk_mul_f32 v[104:105], v[74:75], v[76:77] op_sel_hi:[0,1]
	v_pk_mul_f32 v[72:73], v[74:75], v[72:73] op_sel_hi:[0,1]
	v_pk_mul_f32 v[72:73], v[0:1], v[72:73]
	v_pk_mul_f32 v[104:105], v[2:3], v[104:105]
	v_pk_mul_f32 v[72:73], v[72:73], s[8:9] op_sel_hi:[1,0]
	v_pk_mul_f32 v[104:105], v[104:105], s[8:9] op_sel_hi:[1,0]
	v_cvt_pk_bf16_f32 v72, v72, v73
	v_cvt_pk_bf16_f32 v73, v104, v105
	global_store_dwordx2 v[66:67], v[72:73], off offset:1024
	s_waitcnt vmcnt(4)
; __device__ __forceinline__ unsigned pk2(float lo, float hi) { const f32x2 v = {lo, hi}; const hwbf16x2 b = __builtin_convertvector(v, hwbf16x2); return __builtin_bit_cast(unsigned, b); }
; __device__ __forceinline__ void dsa_prep(const Args& a, unsigned char* lds, int tid) {
;     ...
;             for (int j = 0; j < 5; ++j) {
;                 const int hh = j * 4 + grp, col = hh * 64 + 4 * sub;
;                 const u32x2 x = *(const u32x2*)(src + col);
;                 f32x4 v = (f32x4){bflo(x.x), bfhi(x.x), bflo(x.y), bfhi(x.y)};
;                 float ss = (v.x * v.x + v.y * v.y) + (v.z * v.z + v.w * v.w);
;                 ss = row16_sum(ss);
;                 const float rstd = __builtin_amdgcn_rsqf(ss * (1.f / 64.f) + 1e-6f);
;                 if (j < 4) { v = v * rstd * qn * QSCALE; u32x2 o; o.x = pk2(v.x, v.y); o.y = pk2(v.z, v.w); *(u32x2*)(QN + (size_t)row * D + col) = o; }
;                 else { v = v * rstd * kn; u32x2 o; o.x = pk2(v.x, v.y); o.y = pk2(v.z, v.w); *(u32x2*)(KN + (size_t)row * 256 + (col - 1024)) = o; }
;             }
;             {
;                 const u32x2 x = *(const u32x2*)(src + 2048 + 4 * sub);
;                 f32x4 v = (f32x4){bflo(x.x), bfhi(x.x), bflo(x.y), bfhi(x.y)};
;                 float ss = (v.x * v.x + v.y * v.y) + (v.z * v.z + v.w * v.w);
;                 ss = row16_sum(ss);
;                 const float rstd = __builtin_amdgcn_rsqf(ss * (1.f / 64.f) + 1e-6f);
;                 v = v * rstd * ikn;
;                 if (grp == 0) { u32x2 o; o.x = pk2(v.x, v.y); o.y = pk2(v.z, v.w); *(u32x2*)(IKN + (size_t)row * 64 + 4 * sub) = o; }
	v_lshlrev_b32_e32 v73, 16, v65
	v_lshlrev_b32_e32 v72, 16, v64
	v_and_b32_e32 v65, 0xffff0000, v65
	v_and_b32_e32 v64, 0xffff0000, v64
	v_pk_mul_f32 v[74:75], v[64:65], v[64:65]
	v_mov_b32_e32 v76, v73
	v_pk_fma_f32 v[74:75], v[72:73], v[72:73], v[74:75]
	v_mov_b32_e32 v77, v65
	v_add_f32_e32 v41, v74, v75
	v_mov_b32_e32 v73, v64
	s_nop 0
	v_add_f32_dpp v41, v41, v41 quad_perm:[1,0,3,2] row_mask:0xf bank_mask:0xf bound_ctrl:1
	s_nop 1
	v_add_f32_dpp v41, v41, v41 quad_perm:[2,3,0,1] row_mask:0xf bank_mask:0xf bound_ctrl:1
	s_nop 1
	v_add_f32_dpp v41, v41, v41 row_half_mirror row_mask:0xf bank_mask:0xf bound_ctrl:1
	s_nop 1
	v_add_f32_dpp v41, v41, v41 row_mirror row_mask:0xf bank_mask:0xf bound_ctrl:1
	v_fmamk_f32 v41, v41, 0x3c800000, v23
	v_rsq_f32_e32 v74, v41
	v_mov_b32_e32 v41, v13
	v_pk_mul_f32 v[64:65], v[74:75], v[76:77] op_sel_hi:[0,1]
	v_pk_mul_f32 v[72:73], v[74:75], v[72:73] op_sel_hi:[0,1]
	v_pk_mul_f32 v[72:73], v[0:1], v[72:73]
	v_pk_mul_f32 v[64:65], v[2:3], v[64:65]
	v_pk_mul_f32 v[72:73], v[72:73], s[8:9] op_sel_hi:[1,0]
	v_pk_mul_f32 v[64:65], v[64:65], s[8:9] op_sel_hi:[1,0]
	v_cvt_pk_bf16_f32 v72, v72, v73
	v_cvt_pk_bf16_f32 v73, v64, v65
	global_store_dwordx2 v[66:67], v[72:73], off offset:1536
	v_lshl_add_u64 v[66:67], v[62:63], 0, v[40:41]
	v_lshlrev_b64 v[64:65], 9, v[60:61]
	v_add_co_u32_e32 v66, vcc, s9, v66
	v_lshl_add_u64 v[64:65], v[24:25], 0, v[64:65]
	s_nop 0
	v_addc_co_u32_e32 v67, vcc, 0, v67, vcc
	v_add_co_u32_e32 v64, vcc, s21, v64
	s_waitcnt vmcnt(4)
	v_lshlrev_b32_e32 v73, 16, v107
	v_lshlrev_b32_e32 v72, 16, v106
	v_and_b32_e32 v107, 0xffff0000, v107
	v_and_b32_e32 v106, 0xffff0000, v106
	v_pk_mul_f32 v[74:75], v[106:107], v[106:107]
	v_mov_b32_e32 v76, v72
	v_pk_fma_f32 v[74:75], v[72:73], v[72:73], v[74:75]
	v_mov_b32_e32 v77, v106
	v_add_f32_e32 v41, v74, v75
	v_mov_b32_e32 v106, v73
	v_addc_co_u32_e32 v65, vcc, 0, v65, vcc
	v_add_f32_dpp v41, v41, v41 quad_perm:[1,0,3,2] row_mask:0xf bank_mask:0xf bound_ctrl:1
	s_nop 1
	v_add_f32_dpp v41, v41, v41 quad_perm:[2,3,0,1] row_mask:0xf bank_mask:0xf bound_ctrl:1
	s_nop 1
	v_add_f32_dpp v41, v41, v41 row_half_mirror row_mask:0xf bank_mask:0xf bound_ctrl:1
	s_nop 1
	v_add_f32_dpp v41, v41, v41 row_mirror row_mask:0xf bank_mask:0xf bound_ctrl:1
	v_fmamk_f32 v41, v41, 0x3c800000, v23
	v_rsq_f32_e32 v74, v41
	s_nop 0
	v_pk_mul_f32 v[72:73], v[74:75], v[76:77] op_sel_hi:[0,1]
	v_pk_mul_f32 v[106:107], v[74:75], v[106:107] op_sel_hi:[0,1]
	v_pk_mul_f32 v[106:107], v[6:7], v[106:107]
	v_pk_mul_f32 v[72:73], v[4:5], v[72:73]
	s_nop 0
	v_cvt_pk_bf16_f32 v72, v72, v73
	v_cvt_pk_bf16_f32 v73, v106, v107
	global_store_dwordx2 v[64:65], v[72:73], off
	global_load_dwordx2 v[58:59], v[66:67], off
	s_waitcnt vmcnt(0)
	v_lshlrev_b32_e32 v64, 16, v58
	v_and_b32_e32 v65, 0xffff0000, v58
	v_lshlrev_b32_e32 v58, 16, v59
	v_and_b32_e32 v59, 0xffff0000, v59
	v_mul_f32_e32 v41, v65, v65
	v_mul_f32_e32 v43, v59, v59
	v_fmac_f32_e32 v41, v64, v64
	v_fmac_f32_e32 v43, v58, v58
	v_add_f32_e32 v41, v41, v43
	s_nop 1
	v_add_f32_dpp v41, v41, v41 quad_perm:[1,0,3,2] row_mask:0xf bank_mask:0xf bound_ctrl:1
	s_nop 1
	v_add_f32_dpp v41, v41, v41 quad_perm:[2,3,0,1] row_mask:0xf bank_mask:0xf bound_ctrl:1
	s_nop 1
	v_add_f32_dpp v41, v41, v41 row_half_mirror row_mask:0xf bank_mask:0xf bound_ctrl:1
	s_nop 1
	v_mov_b32_dpp v43, v41 row_mirror row_mask:0xf bank_mask:0xf bound_ctrl:1
	s_and_saveexec_b64 s[12:13], s[0:1]
	s_cbranch_execz .LBB0_581
	v_add_f32_e32 v41, v41, v43
	v_fmamk_f32 v41, v41, 0x3c800000, v23
	v_rsq_f32_e32 v66, v41
	s_nop 0
	v_pk_mul_f32 v[64:65], v[64:65], v[66:67] op_sel_hi:[1,0]
	v_pk_mul_f32 v[58:59], v[58:59], v[66:67] op_sel_hi:[1,0]
	v_pk_mul_f32 v[64:65], v[8:9], v[64:65]
	v_pk_mul_f32 v[58:59], v[10:11], v[58:59]
	v_cvt_pk_bf16_f32 v64, v64, v65
	v_cvt_pk_bf16_f32 v65, v58, v59
	v_lshlrev_b64 v[58:59], 7, v[60:61]
	v_lshl_add_u64 v[58:59], v[16:17], 0, v[58:59]
	global_store_dwordx2 v[58:59], v[64:65], off

; __device__ __forceinline__ unsigned pk2(float lo, float hi) { const f32x2 v = {lo, hi}; const hwbf16x2 b = __builtin_convertvector(v, hwbf16x2); return __builtin_bit_cast(unsigned, b); }
; __device__ __forceinline__ void dsa_prep(const Args& a, unsigned char* lds, int tid) {
;     ...
;         for (int i = 0; i < 8; ++i) {
;             const int row = t0 + 8 * w + i;
;             const bf16* src = QKVI + (size_t)row * QKVI_LD;
; #pragma unroll
;             for (int j = 0; j < 5; ++j) {
;                 const int hh = j * 4 + grp, col = hh * 64 + 4 * sub;
;                 const u32x2 x = *(const u32x2*)(src + col);
;                 f32x4 v = (f32x4){bflo(x.x), bfhi(x.x), bflo(x.y), bfhi(x.y)};
;                 float ss = (v.x * v.x + v.y * v.y) + (v.z * v.z + v.w * v.w);
;                 ss = row16_sum(ss);
;                 const float rstd = __builtin_amdgcn_rsqf(ss * (1.f / 64.f) + 1e-6f);
;                 if (j < 4) { v = v * rstd * qn * QSCALE; u32x2 o; o.x = pk2(v.x, v.y); o.y = pk2(v.z, v.w); *(u32x2*)(QN + (size_t)row * D + col) = o; }
;                 else { v = v * rstd * kn; u32x2 o; o.x = pk2(v.x, v.y); o.y = pk2(v.z, v.w); *(u32x2*)(KN + (size_t)row * 256 + (col - 1024)) = o; }
;             }
.LBB0_583:
	s_or_b64 exec, exec, s[12:13]
	v_readlane_b32 s12, v248, 61
	v_readlane_b32 s13, v248, 62
	v_add_u32_e32 v60, 2, v29
	v_ashrrev_i32_e32 v61, 31, v60
	v_mov_b64_e32 v[62:63], s[12:13]
	v_mad_i64_i32 v[62:63], s[12:13], v60, s22, v[62:63]
	v_lshl_add_u64 v[64:65], v[62:63], 0, v[12:13]
	global_load_dwordx2 v[100:101], v[64:65], off
	global_load_dwordx2 v[102:103], v[64:65], off offset:512
	global_load_dwordx2 v[104:105], v[64:65], off offset:1024
	global_load_dwordx2 v[66:67], v[64:65], off offset:1536
	global_load_dwordx2 v[106:107], v[64:65], off offset:2048
	v_lshlrev_b64 v[72:73], 11, v[60:61]
	v_lshl_add_u64 v[72:73], v[26:27], 0, v[72:73]
	s_waitcnt vmcnt(4)
	v_lshlrev_b32_e32 v75, 16, v101
	v_lshlrev_b32_e32 v74, 16, v100
	v_and_b32_e32 v101, 0xffff0000, v101
	v_and_b32_e32 v100, 0xffff0000, v100
	v_pk_mul_f32 v[76:77], v[100:101], v[100:101]
	v_mov_b32_e32 v78, v75
	v_pk_fma_f32 v[76:77], v[74:75], v[74:75], v[76:77]
	v_mov_b32_e32 v79, v101
	v_add_f32_e32 v41, v76, v77
	v_mov_b32_e32 v75, v100
	s_nop 0
	v_add_f32_dpp v41, v41, v41 quad_perm:[1,0,3,2] row_mask:0xf bank_mask:0xf bound_ctrl:1
	s_nop 1
	v_add_f32_dpp v41, v41, v41 quad_perm:[2,3,0,1] row_mask:0xf bank_mask:0xf bound_ctrl:1
	s_nop 1
	v_add_f32_dpp v41, v41, v41 row_half_mirror row_mask:0xf bank_mask:0xf bound_ctrl:1
	s_nop 1
	v_add_f32_dpp v41, v41, v41 row_mirror row_mask:0xf bank_mask:0xf bound_ctrl:1
	v_fmamk_f32 v41, v41, 0x3c800000, v23
	v_rsq_f32_e32 v76, v41
	s_nop 0
	v_pk_mul_f32 v[100:101], v[76:77], v[78:79] op_sel_hi:[0,1]
	v_pk_mul_f32 v[74:75], v[76:77], v[74:75] op_sel_hi:[0,1]
	v_pk_mul_f32 v[74:75], v[0:1], v[74:75]
	v_pk_mul_f32 v[100:101], v[2:3], v[100:101]
	v_pk_mul_f32 v[74:75], v[74:75], s[8:9] op_sel_hi:[1,0]
	v_pk_mul_f32 v[100:101], v[100:101], s[8:9] op_sel_hi:[1,0]
	v_cvt_pk_bf16_f32 v74, v74, v75
	v_cvt_pk_bf16_f32 v75, v100, v101
	global_store_dwordx2 v[72:73], v[74:75], off
	s_waitcnt vmcnt(4)
	v_lshlrev_b32_e32 v75, 16, v103
	v_lshlrev_b32_e32 v74, 16, v102
	v_and_b32_e32 v103, 0xffff0000, v103
	v_and_b32_e32 v102, 0xffff0000, v102
	v_pk_mul_f32 v[76:77], v[102:103], v[102:103]
	v_mov_b32_e32 v78, v75
	v_pk_fma_f32 v[76:77], v[74:75], v[74:75], v[76:77]
	v_mov_b32_e32 v79, v103
	v_add_f32_e32 v41, v76, v77
	v_mov_b32_e32 v75, v102
	s_nop 0
	v_add_f32_dpp v41, v41, v41 quad_perm:[1,0,3,2] row_mask:0xf bank_mask:0xf bound_ctrl:1
	s_nop 1
	v_add_f32_dpp v41, v41, v41 quad_perm:[2,3,0,1] row_mask:0xf bank_mask:0xf bound_ctrl:1
	s_nop 1
	v_add_f32_dpp v41, v41, v41 row_half_mirror row_mask:0xf bank_mask:0xf bound_ctrl:1
	s_nop 1
	v_add_f32_dpp v41, v41, v41 row_mirror row_mask:0xf bank_mask:0xf bound_ctrl:1
	v_fmamk_f32 v41, v41, 0x3c800000, v23
	v_rsq_f32_e32 v76, v41
	s_nop 0
	v_pk_mul_f32 v[102:103], v[76:77], v[78:79] op_sel_hi:[0,1]
	v_pk_mul_f32 v[74:75], v[76:77], v[74:75] op_sel_hi:[0,1]
	v_pk_mul_f32 v[74:75], v[0:1], v[74:75]
	v_pk_mul_f32 v[102:103], v[2:3], v[102:103]
	v_pk_mul_f32 v[74:75], v[74:75], s[8:9] op_sel_hi:[1,0]
	v_pk_mul_f32 v[102:103], v[102:103], s[8:9] op_sel_hi:[1,0]
	v_cvt_pk_bf16_f32 v74, v74, v75
	v_cvt_pk_bf16_f32 v75, v102, v103
	global_store_dwordx2 v[72:73], v[74:75], off offset:512
	s_waitcnt vmcnt(4)
	v_lshlrev_b32_e32 v75, 16, v105
	v_lshlrev_b32_e32 v74, 16, v104
	v_and_b32_e32 v105, 0xffff0000, v105
	v_and_b32_e32 v104, 0xffff0000, v104
	v_pk_mul_f32 v[76:77], v[104:105], v[104:105]
	v_mov_b32_e32 v78, v75
	v_pk_fma_f32 v[76:77], v[74:75], v[74:75], v[76:77]
	v_mov_b32_e32 v79, v105
	v_add_f32_e32 v41, v76, v77
	v_mov_b32_e32 v75, v104
	s_nop 0
	v_add_f32_dpp v41, v41, v41 quad_perm:[1,0,3,2] row_mask:0xf bank_mask:0xf bound_ctrl:1
	s_nop 1
	v_add_f32_dpp v41, v41, v41 quad_perm:[2,3,0,1] row_mask:0xf bank_mask:0xf bound_ctrl:1
	s_nop 1
	v_add_f32_dpp v41, v41, v41 row_half_mirror row_mask:0xf bank_mask:0xf bound_ctrl:1
	s_nop 1
	v_add_f32_dpp v41, v41, v41 row_mirror row_mask:0xf bank_mask:0xf bound_ctrl:1
	v_fmamk_f32 v41, v41, 0x3c800000, v23
	v_rsq_f32_e32 v76, v41
	s_nop 0
	v_pk_mul_f32 v[104:105], v[76:77], v[78:79] op_sel_hi:[0,1]
	v_pk_mul_f32 v[74:75], v[76:77], v[74:75] op_sel_hi:[0,1]
	v_pk_mul_f32 v[74:75], v[0:1], v[74:75]
	v_pk_mul_f32 v[104:105], v[2:3], v[104:105]
	v_pk_mul_f32 v[74:75], v[74:75], s[8:9] op_sel_hi:[1,0]
	v_pk_mul_f32 v[104:105], v[104:105], s[8:9] op_sel_hi:[1,0]
	v_cvt_pk_bf16_f32 v74, v74, v75
	v_cvt_pk_bf16_f32 v75, v104, v105
	global_store_dwordx2 v[72:73], v[74:75], off offset:1024
	s_waitcnt vmcnt(4)
; __device__ __forceinline__ unsigned pk2(float lo, float hi) { const f32x2 v = {lo, hi}; const hwbf16x2 b = __builtin_convertvector(v, hwbf16x2); return __builtin_bit_cast(unsigned, b); }
; __device__ __forceinline__ void dsa_prep(const Args& a, unsigned char* lds, int tid) {
;     ...
;             for (int j = 0; j < 5; ++j) {
;                 const int hh = j * 4 + grp, col = hh * 64 + 4 * sub;
;                 const u32x2 x = *(const u32x2*)(src + col);
;                 f32x4 v = (f32x4){bflo(x.x), bfhi(x.x), bflo(x.y), bfhi(x.y)};
;                 float ss = (v.x * v.x + v.y * v.y) + (v.z * v.z + v.w * v.w);
;                 ss = row16_sum(ss);
;                 const float rstd = __builtin_amdgcn_rsqf(ss * (1.f / 64.f) + 1e-6f);
;                 if (j < 4) { v = v * rstd * qn * QSCALE; u32x2 o; o.x = pk2(v.x, v.y); o.y = pk2(v.z, v.w); *(u32x2*)(QN + (size_t)row * D + col) = o; }
;                 else { v = v * rstd * kn; u32x2 o; o.x = pk2(v.x, v.y); o.y = pk2(v.z, v.w); *(u32x2*)(KN + (size_t)row * 256 + (col - 1024)) = o; }
;             }
;             {
;                 const u32x2 x = *(const u32x2*)(src + 2048 + 4 * sub);
;                 f32x4 v = (f32x4){bflo(x.x), bfhi(x.x), bflo(x.y), bfhi(x.y)};
;                 float ss = (v.x * v.x + v.y * v.y) + (v.z * v.z + v.w * v.w);
;                 ss = row16_sum(ss);
;                 const float rstd = __builtin_amdgcn_rsqf(ss * (1.f / 64.f) + 1e-6f);
;                 v = v * rstd * ikn;
;                 if (grp == 0) { u32x2 o; o.x = pk2(v.x, v.y); o.y = pk2(v.z, v.w); *(u32x2*)(IKN + (size_t)row * 64 + 4 * sub) = o; }
	v_lshlrev_b32_e32 v75, 16, v67
	v_lshlrev_b32_e32 v74, 16, v66
	v_and_b32_e32 v67, 0xffff0000, v67
	v_and_b32_e32 v66, 0xffff0000, v66
	v_pk_mul_f32 v[76:77], v[66:67], v[66:67]
	v_mov_b32_e32 v78, v75
	v_pk_fma_f32 v[76:77], v[74:75], v[74:75], v[76:77]
	v_mov_b32_e32 v79, v67
	v_add_f32_e32 v41, v76, v77
	v_mov_b32_e32 v75, v66
	s_nop 0
	v_add_f32_dpp v41, v41, v41 quad_perm:[1,0,3,2] row_mask:0xf bank_mask:0xf bound_ctrl:1
	s_nop 1
	v_add_f32_dpp v41, v41, v41 quad_perm:[2,3,0,1] row_mask:0xf bank_mask:0xf bound_ctrl:1
	s_nop 1
	v_add_f32_dpp v41, v41, v41 row_half_mirror row_mask:0xf bank_mask:0xf bound_ctrl:1
	s_nop 1
	v_add_f32_dpp v41, v41, v41 row_mirror row_mask:0xf bank_mask:0xf bound_ctrl:1
	v_fmamk_f32 v41, v41, 0x3c800000, v23
	v_rsq_f32_e32 v76, v41
	v_mov_b32_e32 v41, v13
	v_pk_mul_f32 v[66:67], v[76:77], v[78:79] op_sel_hi:[0,1]
	v_pk_mul_f32 v[74:75], v[76:77], v[74:75] op_sel_hi:[0,1]
	v_pk_mul_f32 v[74:75], v[0:1], v[74:75]
	v_pk_mul_f32 v[66:67], v[2:3], v[66:67]
	v_pk_mul_f32 v[74:75], v[74:75], s[8:9] op_sel_hi:[1,0]
	v_pk_mul_f32 v[66:67], v[66:67], s[8:9] op_sel_hi:[1,0]
	v_cvt_pk_bf16_f32 v74, v74, v75
	v_cvt_pk_bf16_f32 v75, v66, v67
	global_store_dwordx2 v[72:73], v[74:75], off offset:1536
	v_lshl_add_u64 v[72:73], v[62:63], 0, v[40:41]
	v_lshlrev_b64 v[66:67], 9, v[60:61]
	v_add_co_u32_e32 v72, vcc, s9, v72
	v_lshl_add_u64 v[66:67], v[24:25], 0, v[66:67]
	s_nop 0
	v_addc_co_u32_e32 v73, vcc, 0, v73, vcc
	v_add_co_u32_e32 v66, vcc, s21, v66
	s_waitcnt vmcnt(4)
	v_lshlrev_b32_e32 v75, 16, v107
	v_lshlrev_b32_e32 v74, 16, v106
	v_and_b32_e32 v107, 0xffff0000, v107
	v_and_b32_e32 v106, 0xffff0000, v106
	v_pk_mul_f32 v[76:77], v[106:107], v[106:107]
	v_mov_b32_e32 v78, v74
	v_pk_fma_f32 v[76:77], v[74:75], v[74:75], v[76:77]
	v_mov_b32_e32 v79, v106
	v_add_f32_e32 v41, v76, v77
	v_mov_b32_e32 v106, v75
	v_addc_co_u32_e32 v67, vcc, 0, v67, vcc
	v_add_f32_dpp v41, v41, v41 quad_perm:[1,0,3,2] row_mask:0xf bank_mask:0xf bound_ctrl:1
	s_nop 1
	v_add_f32_dpp v41, v41, v41 quad_perm:[2,3,0,1] row_mask:0xf bank_mask:0xf bound_ctrl:1
	s_nop 1
	v_add_f32_dpp v41, v41, v41 row_half_mirror row_mask:0xf bank_mask:0xf bound_ctrl:1
	s_nop 1
	v_add_f32_dpp v41, v41, v41 row_mirror row_mask:0xf bank_mask:0xf bound_ctrl:1
	v_fmamk_f32 v41, v41, 0x3c800000, v23
	v_rsq_f32_e32 v76, v41
	s_nop 0
	v_pk_mul_f32 v[74:75], v[76:77], v[78:79] op_sel_hi:[0,1]
	v_pk_mul_f32 v[106:107], v[76:77], v[106:107] op_sel_hi:[0,1]
	v_pk_mul_f32 v[106:107], v[6:7], v[106:107]
	v_pk_mul_f32 v[74:75], v[4:5], v[74:75]
	s_nop 0
	v_cvt_pk_bf16_f32 v74, v74, v75
	v_cvt_pk_bf16_f32 v75, v106, v107
	global_store_dwordx2 v[66:67], v[74:75], off
	global_load_dwordx2 v[64:65], v[72:73], off
	s_waitcnt vmcnt(0)
	v_lshlrev_b32_e32 v66, 16, v64
	v_and_b32_e32 v67, 0xffff0000, v64
	v_lshlrev_b32_e32 v64, 16, v65
	v_and_b32_e32 v65, 0xffff0000, v65
	v_mul_f32_e32 v41, v67, v67
	v_mul_f32_e32 v43, v65, v65
	v_fmac_f32_e32 v41, v66, v66
	v_fmac_f32_e32 v43, v64, v64
	v_add_f32_e32 v41, v41, v43
	s_nop 1
	v_add_f32_dpp v41, v41, v41 quad_perm:[1,0,3,2] row_mask:0xf bank_mask:0xf bound_ctrl:1
	s_nop 1
	v_add_f32_dpp v41, v41, v41 quad_perm:[2,3,0,1] row_mask:0xf bank_mask:0xf bound_ctrl:1
	s_nop 1
	v_add_f32_dpp v41, v41, v41 row_half_mirror row_mask:0xf bank_mask:0xf bound_ctrl:1
	s_nop 1
	v_mov_b32_dpp v43, v41 row_mirror row_mask:0xf bank_mask:0xf bound_ctrl:1
	s_and_saveexec_b64 s[12:13], s[0:1]
	s_cbranch_execz .LBB0_585
	v_add_f32_e32 v41, v41, v43
	v_fmamk_f32 v41, v41, 0x3c800000, v23
	v_rsq_f32_e32 v72, v41
	s_nop 0
	v_pk_mul_f32 v[66:67], v[66:67], v[72:73] op_sel_hi:[1,0]
	v_pk_mul_f32 v[64:65], v[64:65], v[72:73] op_sel_hi:[1,0]
	v_pk_mul_f32 v[66:67], v[8:9], v[66:67]
	v_pk_mul_f32 v[64:65], v[10:11], v[64:65]
	v_cvt_pk_bf16_f32 v66, v66, v67
	v_cvt_pk_bf16_f32 v67, v64, v65
	v_lshlrev_b64 v[64:65], 7, v[60:61]
	v_lshl_add_u64 v[64:65], v[16:17], 0, v[64:65]
	global_store_dwordx2 v[64:65], v[66:67], off

; __device__ __forceinline__ unsigned pk2(float lo, float hi) { const f32x2 v = {lo, hi}; const hwbf16x2 b = __builtin_convertvector(v, hwbf16x2); return __builtin_bit_cast(unsigned, b); }
; __device__ __forceinline__ void dsa_prep(const Args& a, unsigned char* lds, int tid) {
;     ...
;         for (int i = 0; i < 8; ++i) {
;             const int row = t0 + 8 * w + i;
;             const bf16* src = QKVI + (size_t)row * QKVI_LD;
; #pragma unroll
;             for (int j = 0; j < 5; ++j) {
;                 const int hh = j * 4 + grp, col = hh * 64 + 4 * sub;
;                 const u32x2 x = *(const u32x2*)(src + col);
;                 f32x4 v = (f32x4){bflo(x.x), bfhi(x.x), bflo(x.y), bfhi(x.y)};
;                 float ss = (v.x * v.x + v.y * v.y) + (v.z * v.z + v.w * v.w);
;                 ss = row16_sum(ss);
;                 const float rstd = __builtin_amdgcn_rsqf(ss * (1.f / 64.f) + 1e-6f);
;                 if (j < 4) { v = v * rstd * qn * QSCALE; u32x2 o; o.x = pk2(v.x, v.y); o.y = pk2(v.z, v.w); *(u32x2*)(QN + (size_t)row * D + col) = o; }
;                 else { v = v * rstd * kn; u32x2 o; o.x = pk2(v.x, v.y); o.y = pk2(v.z, v.w); *(u32x2*)(KN + (size_t)row * 256 + (col - 1024)) = o; }
;             }
.LBB0_587:
	s_or_b64 exec, exec, s[12:13]
	v_readlane_b32 s12, v248, 61
	v_readlane_b32 s13, v248, 62
	v_add_u32_e32 v60, 3, v29
	v_ashrrev_i32_e32 v61, 31, v60
	v_mov_b64_e32 v[62:63], s[12:13]
	v_mad_i64_i32 v[62:63], s[12:13], v60, s22, v[62:63]
	v_lshl_add_u64 v[64:65], v[62:63], 0, v[12:13]
	global_load_dwordx2 v[100:101], v[64:65], off
	global_load_dwordx2 v[102:103], v[64:65], off offset:512
	global_load_dwordx2 v[104:105], v[64:65], off offset:1024
	global_load_dwordx2 v[66:67], v[64:65], off offset:1536
	global_load_dwordx2 v[106:107], v[64:65], off offset:2048
	v_lshlrev_b64 v[72:73], 11, v[60:61]
	v_lshl_add_u64 v[72:73], v[26:27], 0, v[72:73]
	v_mov_b32_e32 v41, v13
	s_waitcnt vmcnt(4)
	v_lshlrev_b32_e32 v75, 16, v101
	v_lshlrev_b32_e32 v74, 16, v100
	v_and_b32_e32 v101, 0xffff0000, v101
	v_and_b32_e32 v100, 0xffff0000, v100
	v_pk_mul_f32 v[76:77], v[100:101], v[100:101]
	v_mov_b32_e32 v78, v75
	v_pk_fma_f32 v[76:77], v[74:75], v[74:75], v[76:77]
	v_mov_b32_e32 v79, v101
	v_add_f32_e32 v29, v76, v77
	v_mov_b32_e32 v75, v100
	s_nop 0
	v_add_f32_dpp v29, v29, v29 quad_perm:[1,0,3,2] row_mask:0xf bank_mask:0xf bound_ctrl:1
	s_nop 1
	v_add_f32_dpp v29, v29, v29 quad_perm:[2,3,0,1] row_mask:0xf bank_mask:0xf bound_ctrl:1
	s_nop 1
	v_add_f32_dpp v29, v29, v29 row_half_mirror row_mask:0xf bank_mask:0xf bound_ctrl:1
	s_nop 1
	v_add_f32_dpp v29, v29, v29 row_mirror row_mask:0xf bank_mask:0xf bound_ctrl:1
	v_fmamk_f32 v29, v29, 0x3c800000, v23
	v_rsq_f32_e32 v76, v29
	s_nop 0
	v_pk_mul_f32 v[100:101], v[76:77], v[78:79] op_sel_hi:[0,1]
	v_pk_mul_f32 v[74:75], v[76:77], v[74:75] op_sel_hi:[0,1]
	v_pk_mul_f32 v[74:75], v[0:1], v[74:75]
	v_pk_mul_f32 v[100:101], v[2:3], v[100:101]
	v_pk_mul_f32 v[74:75], v[74:75], s[8:9] op_sel_hi:[1,0]
	v_pk_mul_f32 v[100:101], v[100:101], s[8:9] op_sel_hi:[1,0]
	v_cvt_pk_bf16_f32 v74, v74, v75
	v_cvt_pk_bf16_f32 v75, v100, v101
	global_store_dwordx2 v[72:73], v[74:75], off
	s_waitcnt vmcnt(4)
	v_lshlrev_b32_e32 v75, 16, v103
	v_lshlrev_b32_e32 v74, 16, v102
	v_and_b32_e32 v103, 0xffff0000, v103
	v_and_b32_e32 v102, 0xffff0000, v102
	v_pk_mul_f32 v[76:77], v[102:103], v[102:103]
	v_mov_b32_e32 v78, v75
	v_pk_fma_f32 v[76:77], v[74:75], v[74:75], v[76:77]
	v_mov_b32_e32 v79, v103
	v_add_f32_e32 v29, v76, v77
	v_mov_b32_e32 v75, v102
	s_nop 0
	v_add_f32_dpp v29, v29, v29 quad_perm:[1,0,3,2] row_mask:0xf bank_mask:0xf bound_ctrl:1
	s_nop 1
	v_add_f32_dpp v29, v29, v29 quad_perm:[2,3,0,1] row_mask:0xf bank_mask:0xf bound_ctrl:1
	s_nop 1
	v_add_f32_dpp v29, v29, v29 row_half_mirror row_mask:0xf bank_mask:0xf bound_ctrl:1
	s_nop 1
	v_add_f32_dpp v29, v29, v29 row_mirror row_mask:0xf bank_mask:0xf bound_ctrl:1
	v_fmamk_f32 v29, v29, 0x3c800000, v23
	v_rsq_f32_e32 v76, v29
	s_nop 0
	v_pk_mul_f32 v[102:103], v[76:77], v[78:79] op_sel_hi:[0,1]
	v_pk_mul_f32 v[74:75], v[76:77], v[74:75] op_sel_hi:[0,1]
	v_pk_mul_f32 v[74:75], v[0:1], v[74:75]
	v_pk_mul_f32 v[102:103], v[2:3], v[102:103]
	v_pk_mul_f32 v[74:75], v[74:75], s[8:9] op_sel_hi:[1,0]
	v_pk_mul_f32 v[102:103], v[102:103], s[8:9] op_sel_hi:[1,0]
	v_cvt_pk_bf16_f32 v74, v74, v75
	v_cvt_pk_bf16_f32 v75, v102, v103
	global_store_dwordx2 v[72:73], v[74:75], off offset:512
	s_waitcnt vmcnt(4)
	v_lshlrev_b32_e32 v75, 16, v105
	v_lshlrev_b32_e32 v74, 16, v104
	v_and_b32_e32 v105, 0xffff0000, v105
	v_and_b32_e32 v104, 0xffff0000, v104
	v_pk_mul_f32 v[76:77], v[104:105], v[104:105]
	v_mov_b32_e32 v78, v75
	v_pk_fma_f32 v[76:77], v[74:75], v[74:75], v[76:77]
	v_mov_b32_e32 v79, v105
	v_add_f32_e32 v29, v76, v77
	v_mov_b32_e32 v75, v104
	s_nop 0
	v_add_f32_dpp v29, v29, v29 quad_perm:[1,0,3,2] row_mask:0xf bank_mask:0xf bound_ctrl:1
	s_nop 1
	v_add_f32_dpp v29, v29, v29 quad_perm:[2,3,0,1] row_mask:0xf bank_mask:0xf bound_ctrl:1
	s_nop 1
	v_add_f32_dpp v29, v29, v29 row_half_mirror row_mask:0xf bank_mask:0xf bound_ctrl:1
	s_nop 1
	v_add_f32_dpp v29, v29, v29 row_mirror row_mask:0xf bank_mask:0xf bound_ctrl:1
	v_fmamk_f32 v29, v29, 0x3c800000, v23
	v_rsq_f32_e32 v76, v29
	s_nop 0
	v_pk_mul_f32 v[104:105], v[76:77], v[78:79] op_sel_hi:[0,1]
	v_pk_mul_f32 v[74:75], v[76:77], v[74:75] op_sel_hi:[0,1]
	v_pk_mul_f32 v[74:75], v[0:1], v[74:75]
	v_pk_mul_f32 v[104:105], v[2:3], v[104:105]
	v_pk_mul_f32 v[74:75], v[74:75], s[8:9] op_sel_hi:[1,0]
	v_pk_mul_f32 v[104:105], v[104:105], s[8:9] op_sel_hi:[1,0]
	v_cvt_pk_bf16_f32 v74, v74, v75
	v_cvt_pk_bf16_f32 v75, v104, v105
	global_store_dwordx2 v[72:73], v[74:75], off offset:1024
	s_waitcnt vmcnt(4)
; __device__ __forceinline__ unsigned pk2(float lo, float hi) { const f32x2 v = {lo, hi}; const hwbf16x2 b = __builtin_convertvector(v, hwbf16x2); return __builtin_bit_cast(unsigned, b); }
; __device__ __forceinline__ void dsa_prep(const Args& a, unsigned char* lds, int tid) {
;     ...
;             for (int j = 0; j < 5; ++j) {
;                 const int hh = j * 4 + grp, col = hh * 64 + 4 * sub;
;                 const u32x2 x = *(const u32x2*)(src + col);
;                 f32x4 v = (f32x4){bflo(x.x), bfhi(x.x), bflo(x.y), bfhi(x.y)};
;                 float ss = (v.x * v.x + v.y * v.y) + (v.z * v.z + v.w * v.w);
;                 ss = row16_sum(ss);
;                 const float rstd = __builtin_amdgcn_rsqf(ss * (1.f / 64.f) + 1e-6f);
;                 if (j < 4) { v = v * rstd * qn * QSCALE; u32x2 o; o.x = pk2(v.x, v.y); o.y = pk2(v.z, v.w); *(u32x2*)(QN + (size_t)row * D + col) = o; }
;                 else { v = v * rstd * kn; u32x2 o; o.x = pk2(v.x, v.y); o.y = pk2(v.z, v.w); *(u32x2*)(KN + (size_t)row * 256 + (col - 1024)) = o; }
;             }
;             {
;                 const u32x2 x = *(const u32x2*)(src + 2048 + 4 * sub);
;                 f32x4 v = (f32x4){bflo(x.x), bfhi(x.x), bflo(x.y), bfhi(x.y)};
;                 float ss = (v.x * v.x + v.y * v.y) + (v.z * v.z + v.w * v.w);
;                 ss = row16_sum(ss);
;                 const float rstd = __builtin_amdgcn_rsqf(ss * (1.f / 64.f) + 1e-6f);
;                 v = v * rstd * ikn;
;                 if (grp == 0) { u32x2 o; o.x = pk2(v.x, v.y); o.y = pk2(v.z, v.w); *(u32x2*)(IKN + (size_t)row * 64 + 4 * sub) = o; }
	v_lshlrev_b32_e32 v75, 16, v67
	v_lshlrev_b32_e32 v74, 16, v66
	v_and_b32_e32 v67, 0xffff0000, v67
	v_and_b32_e32 v66, 0xffff0000, v66
	v_pk_mul_f32 v[76:77], v[66:67], v[66:67]
	v_mov_b32_e32 v78, v75
	v_pk_fma_f32 v[76:77], v[74:75], v[74:75], v[76:77]
	v_mov_b32_e32 v79, v67
	v_add_f32_e32 v29, v76, v77
	v_mov_b32_e32 v75, v66
	s_nop 0
	v_add_f32_dpp v29, v29, v29 quad_perm:[1,0,3,2] row_mask:0xf bank_mask:0xf bound_ctrl:1
	s_nop 1
	v_add_f32_dpp v29, v29, v29 quad_perm:[2,3,0,1] row_mask:0xf bank_mask:0xf bound_ctrl:1
	s_nop 1
	v_add_f32_dpp v29, v29, v29 row_half_mirror row_mask:0xf bank_mask:0xf bound_ctrl:1
	s_nop 1
	v_add_f32_dpp v29, v29, v29 row_mirror row_mask:0xf bank_mask:0xf bound_ctrl:1
	v_fmamk_f32 v29, v29, 0x3c800000, v23
	v_rsq_f32_e32 v76, v29
	s_nop 0
	v_pk_mul_f32 v[66:67], v[76:77], v[78:79] op_sel_hi:[0,1]
	v_pk_mul_f32 v[74:75], v[76:77], v[74:75] op_sel_hi:[0,1]
	v_pk_mul_f32 v[74:75], v[0:1], v[74:75]
	v_pk_mul_f32 v[66:67], v[2:3], v[66:67]
	v_pk_mul_f32 v[74:75], v[74:75], s[8:9] op_sel_hi:[1,0]
	v_pk_mul_f32 v[66:67], v[66:67], s[8:9] op_sel_hi:[1,0]
	v_cvt_pk_bf16_f32 v74, v74, v75
	v_cvt_pk_bf16_f32 v75, v66, v67
	global_store_dwordx2 v[72:73], v[74:75], off offset:1536
	v_lshl_add_u64 v[72:73], v[62:63], 0, v[40:41]
	v_lshlrev_b64 v[66:67], 9, v[60:61]
	v_add_co_u32_e32 v72, vcc, s9, v72
	v_lshl_add_u64 v[66:67], v[24:25], 0, v[66:67]
	s_nop 0
	v_addc_co_u32_e32 v73, vcc, 0, v73, vcc
	v_add_co_u32_e32 v66, vcc, s21, v66
	s_waitcnt vmcnt(4)
	v_lshlrev_b32_e32 v75, 16, v107
	v_lshlrev_b32_e32 v74, 16, v106
	v_and_b32_e32 v107, 0xffff0000, v107
	v_and_b32_e32 v106, 0xffff0000, v106
	v_pk_mul_f32 v[76:77], v[106:107], v[106:107]
	v_mov_b32_e32 v78, v74
	v_pk_fma_f32 v[76:77], v[74:75], v[74:75], v[76:77]
	v_mov_b32_e32 v79, v106
	v_add_f32_e32 v29, v76, v77
	v_mov_b32_e32 v106, v75
	v_addc_co_u32_e32 v67, vcc, 0, v67, vcc
	v_add_f32_dpp v29, v29, v29 quad_perm:[1,0,3,2] row_mask:0xf bank_mask:0xf bound_ctrl:1
	s_nop 1
	v_add_f32_dpp v29, v29, v29 quad_perm:[2,3,0,1] row_mask:0xf bank_mask:0xf bound_ctrl:1
	s_nop 1
	v_add_f32_dpp v29, v29, v29 row_half_mirror row_mask:0xf bank_mask:0xf bound_ctrl:1
	s_nop 1
	v_add_f32_dpp v29, v29, v29 row_mirror row_mask:0xf bank_mask:0xf bound_ctrl:1
	v_fmamk_f32 v29, v29, 0x3c800000, v23
	v_rsq_f32_e32 v76, v29
	s_nop 0
	v_pk_mul_f32 v[74:75], v[76:77], v[78:79] op_sel_hi:[0,1]
	v_pk_mul_f32 v[106:107], v[76:77], v[106:107] op_sel_hi:[0,1]
	v_pk_mul_f32 v[106:107], v[6:7], v[106:107]
	v_pk_mul_f32 v[74:75], v[4:5], v[74:75]
	s_nop 0
	v_cvt_pk_bf16_f32 v74, v74, v75
	v_cvt_pk_bf16_f32 v75, v106, v107
	global_store_dwordx2 v[66:67], v[74:75], off
	global_load_dwordx2 v[64:65], v[72:73], off
	s_waitcnt vmcnt(0)
	v_lshlrev_b32_e32 v66, 16, v64
	v_and_b32_e32 v67, 0xffff0000, v64
	v_lshlrev_b32_e32 v64, 16, v65
	v_and_b32_e32 v65, 0xffff0000, v65
	v_mul_f32_e32 v29, v67, v67
	v_mul_f32_e32 v41, v65, v65
	v_fmac_f32_e32 v29, v66, v66
	v_fmac_f32_e32 v41, v64, v64
	v_add_f32_e32 v29, v29, v41
	s_nop 1
	v_add_f32_dpp v29, v29, v29 quad_perm:[1,0,3,2] row_mask:0xf bank_mask:0xf bound_ctrl:1
	s_nop 1
	v_add_f32_dpp v29, v29, v29 quad_perm:[2,3,0,1] row_mask:0xf bank_mask:0xf bound_ctrl:1
	s_nop 1
	v_add_f32_dpp v29, v29, v29 row_half_mirror row_mask:0xf bank_mask:0xf bound_ctrl:1
	s_nop 1
	v_mov_b32_dpp v41, v29 row_mirror row_mask:0xf bank_mask:0xf bound_ctrl:1
	s_and_saveexec_b64 s[12:13], s[0:1]
	s_cbranch_execz .LBB0_589
	v_add_f32_e32 v29, v29, v41
	v_fmamk_f32 v29, v29, 0x3c800000, v23
	v_rsq_f32_e32 v72, v29
	s_nop 0
	v_pk_mul_f32 v[66:67], v[66:67], v[72:73] op_sel_hi:[1,0]
	v_pk_mul_f32 v[64:65], v[64:65], v[72:73] op_sel_hi:[1,0]
	v_pk_mul_f32 v[66:67], v[8:9], v[66:67]
	v_pk_mul_f32 v[64:65], v[10:11], v[64:65]
	v_cvt_pk_bf16_f32 v66, v66, v67
	v_cvt_pk_bf16_f32 v67, v64, v65
	v_lshlrev_b64 v[64:65], 7, v[60:61]
	v_lshl_add_u64 v[64:65], v[16:17], 0, v[64:65]
	global_store_dwordx2 v[64:65], v[66:67], off
